# transposer with dwordx4 loads + hand-written combine (both layers)
# baseline (speedup 1.0000x reference)
.LBB0_130:
	s_or_b64 exec, exec, s[0:1]
	s_load_dwordx2 s[0:1], s[92:93], 0x58
	s_load_dwordx2 s[2:3], s[92:93], 0xb8
	s_load_dwordx2 s[4:5], s[92:93], 0xc0
	s_load_dwordx2 s[6:7], s[92:93], 0xc8
	s_load_dwordx2 s[8:9], s[92:93], 0xd0
	s_load_dwordx2 s[10:11], s[92:93], 0xe8
	v_and_b32_e32 v74, 63, v154
	v_lshrrev_b32_e32 v75, 6, v154
	v_mul_u32_u24_e32 v75, 0x2100, v75
	v_lshrrev_b32_e32 v3, 5, v74
	v_and_b32_e32 v4, 31, v74
	v_lshlrev_b32_e32 v4, 2, v4
	v_lshrrev_b32_e32 v5, 3, v74
	v_and_b32_e32 v6, 7, v74
	v_mul_u32_u24_e32 v2, 264, v6
	v_add_u32_e32 v2, v2, v5
	v_lshl_add_u32 v2, v2, 2, v75
	v_lshlrev_b32_e32 v6, 4, v6
	v_mul_u32_u24_e32 v1, 132, v5
	v_add3_u32 v1, v1, v6, v75
	v_readfirstlane_b32 s13, v154
	s_lshr_b32 s13, s13, 6
	s_lshl_b32 s26, s96, 3
	s_add_u32 s13, s13, s26
	s_mov_b32 s12, s13
	s_waitcnt lgkmcnt(0)
	s_cmp_ge_u32 s12, 33280
	s_cselect_b32 s41, 1, 0
	s_cselect_b32 s26, 33280, 0
	s_sub_u32 s42, s12, s26
	s_cmp_ge_u32 s42, 12288
	s_cbranch_scc1 .Ltr_m2
	s_mul_i32 s43, s42, 43691
	s_lshr_b32 s43, s43, 24
	s_mul_i32 s26, s43, 384
	s_sub_u32 s44, s42, s26
	s_mov_b32 s14, s0
	s_mov_b32 s15, s1
	s_mov_b32 s36, 0xc000
	s_mov_b32 s37, 0x6000000
	s_mov_b32 s38, 0x0
	s_mov_b32 s39, 0x3000000
	s_mov_b32 s40, 0x1000
	s_branch .Ltr_dec_done1

.Ltr_dec_done1:
	s_mul_i32 s26, s41, s37
	s_lshl_b32 s27, s43, 6
	s_mul_i32 s27, s27, s36
	s_add_u32 s26, s26, s27
	s_lshl_b32 s27, s44, 7
	s_add_u32 s26, s26, s27
	s_add_u32 s14, s14, s26
	s_addc_u32 s15, s15, 0
	s_mul_i32 s26, s41, s39
	s_add_u32 s26, s26, s38
	s_lshl_b32 s27, s44, 5
	s_mul_i32 s27, s27, s40
	s_add_u32 s26, s26, s27
	s_lshl_b32 s27, s43, 7
	s_add_u32 s26, s26, s27
	s_add_u32 s18, s90, s26
	s_addc_u32 s19, s91, 0
	s_mov_b32 s22, s40
	v_mad_u32_u24 v7, v5, s36, v6
	s_lshl_b32 s45, s36, 3
	global_load_dwordx4 v[10:13], v7, s[14:15]
	s_add_u32 s14, s14, s45
	s_addc_u32 s15, s15, 0
	global_load_dwordx4 v[14:17], v7, s[14:15]
	s_add_u32 s14, s14, s45
	s_addc_u32 s15, s15, 0
	global_load_dwordx4 v[18:21], v7, s[14:15]
	s_add_u32 s14, s14, s45
	s_addc_u32 s15, s15, 0
	global_load_dwordx4 v[22:25], v7, s[14:15]
	s_add_u32 s14, s14, s45
	s_addc_u32 s15, s15, 0
	global_load_dwordx4 v[26:29], v7, s[14:15]
	s_add_u32 s14, s14, s45
	s_addc_u32 s15, s15, 0
	global_load_dwordx4 v[30:33], v7, s[14:15]
	s_add_u32 s14, s14, s45
	s_addc_u32 s15, s15, 0
	global_load_dwordx4 v[34:37], v7, s[14:15]
	s_add_u32 s14, s14, s45
	s_addc_u32 s15, s15, 0
	global_load_dwordx4 v[38:41], v7, s[14:15]

.Ltr_dec_done10:
	s_mul_i32 s26, s41, s37
	s_lshl_b32 s27, s43, 6
	s_mul_i32 s27, s27, s36
	s_add_u32 s26, s26, s27
	s_lshl_b32 s27, s44, 7
	s_add_u32 s26, s26, s27
	s_add_u32 s16, s16, s26
	s_addc_u32 s17, s17, 0
	s_mul_i32 s26, s41, s39
	s_add_u32 s26, s26, s38
	s_lshl_b32 s27, s44, 5
	s_mul_i32 s27, s27, s40
	s_add_u32 s26, s26, s27
	s_lshl_b32 s27, s43, 7
	s_add_u32 s26, s26, s27
	s_add_u32 s20, s90, s26
	s_addc_u32 s21, s91, 0
	s_mov_b32 s23, s40
	v_mad_u32_u24 v8, v5, s36, v6
	s_lshl_b32 s45, s36, 3
	global_load_dwordx4 v[42:45], v8, s[16:17]
	s_add_u32 s16, s16, s45
	s_addc_u32 s17, s17, 0
	global_load_dwordx4 v[46:49], v8, s[16:17]
	s_add_u32 s16, s16, s45
	s_addc_u32 s17, s17, 0
	global_load_dwordx4 v[50:53], v8, s[16:17]
	s_add_u32 s16, s16, s45
	s_addc_u32 s17, s17, 0
	global_load_dwordx4 v[54:57], v8, s[16:17]
	s_add_u32 s16, s16, s45
	s_addc_u32 s17, s17, 0
	global_load_dwordx4 v[58:61], v8, s[16:17]
	s_add_u32 s16, s16, s45
	s_addc_u32 s17, s17, 0
	global_load_dwordx4 v[62:65], v8, s[16:17]
	s_add_u32 s16, s16, s45
	s_addc_u32 s17, s17, 0
	global_load_dwordx4 v[66:69], v8, s[16:17]
	s_add_u32 s16, s16, s45
	s_addc_u32 s17, s17, 0
	global_load_dwordx4 v[70:73], v8, s[16:17]
	s_waitcnt vmcnt(8)
	s_branch .Ltr_after9

.Ltr_after9:
	ds_write_b32 v1, v10 offset:0
	ds_write_b32 v1, v11 offset:4
	ds_write_b32 v1, v12 offset:8
	ds_write_b32 v1, v13 offset:12
	ds_write_b32 v1, v14 offset:1056
	ds_write_b32 v1, v15 offset:1060
	ds_write_b32 v1, v16 offset:1064
	ds_write_b32 v1, v17 offset:1068
	ds_write_b32 v1, v18 offset:2112
	ds_write_b32 v1, v19 offset:2116
	ds_write_b32 v1, v20 offset:2120
	ds_write_b32 v1, v21 offset:2124
	ds_write_b32 v1, v22 offset:3168
	ds_write_b32 v1, v23 offset:3172
	ds_write_b32 v1, v24 offset:3176
	ds_write_b32 v1, v25 offset:3180
	ds_write_b32 v1, v26 offset:4224
	ds_write_b32 v1, v27 offset:4228
	ds_write_b32 v1, v28 offset:4232
	ds_write_b32 v1, v29 offset:4236
	ds_write_b32 v1, v30 offset:5280
	ds_write_b32 v1, v31 offset:5284
	ds_write_b32 v1, v32 offset:5288
	ds_write_b32 v1, v33 offset:5292
	ds_write_b32 v1, v34 offset:6336
	ds_write_b32 v1, v35 offset:6340
	ds_write_b32 v1, v36 offset:6344
	ds_write_b32 v1, v37 offset:6348
	ds_write_b32 v1, v38 offset:7392
	ds_write_b32 v1, v39 offset:7396
	ds_write_b32 v1, v40 offset:7400
	ds_write_b32 v1, v41 offset:7404
	v_mad_u32_u24 v9, v5, s22, v6
	s_lshl_b32 s46, s22, 3
	s_waitcnt lgkmcnt(0)
	ds_read_b32 v74, v2 offset:0
	ds_read_b32 v75, v2 offset:132
	ds_read_b32 v76, v2 offset:264
	ds_read_b32 v77, v2 offset:396
	ds_read_b32 v78, v2 offset:528
	ds_read_b32 v79, v2 offset:660
	ds_read_b32 v80, v2 offset:792
	ds_read_b32 v81, v2 offset:924
	ds_read_b32 v82, v2 offset:32
	ds_read_b32 v83, v2 offset:164
	ds_read_b32 v84, v2 offset:296
	ds_read_b32 v85, v2 offset:428
	ds_read_b32 v86, v2 offset:560
	ds_read_b32 v87, v2 offset:692
	ds_read_b32 v88, v2 offset:824
	ds_read_b32 v89, v2 offset:956
	s_waitcnt lgkmcnt(8)
	v_cvt_pk_bf16_f32 v106, v74, v75
	v_cvt_pk_bf16_f32 v107, v76, v77
	v_cvt_pk_bf16_f32 v108, v78, v79
	v_cvt_pk_bf16_f32 v109, v80, v81
	global_store_dwordx4 v9, v[106:109], s[18:19]
	s_add_u32 s18, s18, s46
	s_addc_u32 s19, s19, 0
	ds_read_b32 v90, v2 offset:64
	ds_read_b32 v91, v2 offset:196
	ds_read_b32 v92, v2 offset:328
	ds_read_b32 v93, v2 offset:460
	ds_read_b32 v94, v2 offset:592
	ds_read_b32 v95, v2 offset:724
	ds_read_b32 v96, v2 offset:856
	ds_read_b32 v97, v2 offset:988
	s_waitcnt lgkmcnt(8)
	v_cvt_pk_bf16_f32 v110, v82, v83
	v_cvt_pk_bf16_f32 v111, v84, v85
	v_cvt_pk_bf16_f32 v112, v86, v87
	v_cvt_pk_bf16_f32 v113, v88, v89
	global_store_dwordx4 v9, v[110:113], s[18:19]
	s_add_u32 s18, s18, s46
	s_addc_u32 s19, s19, 0
	ds_read_b32 v98, v2 offset:96
	ds_read_b32 v99, v2 offset:228
	ds_read_b32 v100, v2 offset:360
	ds_read_b32 v101, v2 offset:492
	ds_read_b32 v102, v2 offset:624
	ds_read_b32 v103, v2 offset:756
	ds_read_b32 v104, v2 offset:888
	ds_read_b32 v105, v2 offset:1020
	s_waitcnt lgkmcnt(8)
	v_cvt_pk_bf16_f32 v106, v90, v91
	v_cvt_pk_bf16_f32 v107, v92, v93
	v_cvt_pk_bf16_f32 v108, v94, v95
	v_cvt_pk_bf16_f32 v109, v96, v97
	global_store_dwordx4 v9, v[106:109], s[18:19]
	s_add_u32 s18, s18, s46
	s_addc_u32 s19, s19, 0
	s_waitcnt lgkmcnt(0)
	v_cvt_pk_bf16_f32 v110, v98, v99
	v_cvt_pk_bf16_f32 v111, v100, v101
	v_cvt_pk_bf16_f32 v112, v102, v103
	v_cvt_pk_bf16_f32 v113, v104, v105
	global_store_dwordx4 v9, v[110:113], s[18:19]
	s_cmp_eq_u32 s24, 0
	s_cbranch_scc1 .Ltr_done
	s_add_u32 s12, s12, 2048
	s_cmp_lt_u32 s12, 66560
	s_cselect_b32 s24, 1, 0
	s_cbranch_scc0 .Ltr_nonext17
	s_cmp_ge_u32 s12, 33280
	s_cselect_b32 s41, 1, 0
	s_cselect_b32 s26, 33280, 0
	s_sub_u32 s42, s12, s26
	s_cmp_ge_u32 s42, 12288
	s_cbranch_scc1 .Ltr_m20
	s_mul_i32 s43, s42, 43691
	s_lshr_b32 s43, s43, 24
	s_mul_i32 s26, s43, 384
	s_sub_u32 s44, s42, s26
	s_mov_b32 s14, s0
	s_mov_b32 s15, s1
	s_mov_b32 s36, 0xc000
	s_mov_b32 s37, 0x6000000
	s_mov_b32 s38, 0x0
	s_mov_b32 s39, 0x3000000
	s_mov_b32 s40, 0x1000
	s_branch .Ltr_dec_done19

.Ltr_dec_done19:
	s_mul_i32 s26, s41, s37
	s_lshl_b32 s27, s43, 6
	s_mul_i32 s27, s27, s36
	s_add_u32 s26, s26, s27
	s_lshl_b32 s27, s44, 7
	s_add_u32 s26, s26, s27
	s_add_u32 s14, s14, s26
	s_addc_u32 s15, s15, 0
	s_mul_i32 s26, s41, s39
	s_add_u32 s26, s26, s38
	s_lshl_b32 s27, s44, 5
	s_mul_i32 s27, s27, s40
	s_add_u32 s26, s26, s27
	s_lshl_b32 s27, s43, 7
	s_add_u32 s26, s26, s27
	s_add_u32 s18, s90, s26
	s_addc_u32 s19, s91, 0
	s_mov_b32 s22, s40
	v_mad_u32_u24 v7, v5, s36, v6
	s_lshl_b32 s45, s36, 3
	global_load_dwordx4 v[10:13], v7, s[14:15]
	s_add_u32 s14, s14, s45
	s_addc_u32 s15, s15, 0
	global_load_dwordx4 v[14:17], v7, s[14:15]
	s_add_u32 s14, s14, s45
	s_addc_u32 s15, s15, 0
	global_load_dwordx4 v[18:21], v7, s[14:15]
	s_add_u32 s14, s14, s45
	s_addc_u32 s15, s15, 0
	global_load_dwordx4 v[22:25], v7, s[14:15]
	s_add_u32 s14, s14, s45
	s_addc_u32 s15, s15, 0
	global_load_dwordx4 v[26:29], v7, s[14:15]
	s_add_u32 s14, s14, s45
	s_addc_u32 s15, s15, 0
	global_load_dwordx4 v[30:33], v7, s[14:15]
	s_add_u32 s14, s14, s45
	s_addc_u32 s15, s15, 0
	global_load_dwordx4 v[34:37], v7, s[14:15]
	s_add_u32 s14, s14, s45
	s_addc_u32 s15, s15, 0
	global_load_dwordx4 v[38:41], v7, s[14:15]
	s_waitcnt vmcnt(8)
	s_branch .Ltr_after18

.Ltr_after18:
	ds_write_b32 v1, v42 offset:0
	ds_write_b32 v1, v43 offset:4
	ds_write_b32 v1, v44 offset:8
	ds_write_b32 v1, v45 offset:12
	ds_write_b32 v1, v46 offset:1056
	ds_write_b32 v1, v47 offset:1060
	ds_write_b32 v1, v48 offset:1064
	ds_write_b32 v1, v49 offset:1068
	ds_write_b32 v1, v50 offset:2112
	ds_write_b32 v1, v51 offset:2116
	ds_write_b32 v1, v52 offset:2120
	ds_write_b32 v1, v53 offset:2124
	ds_write_b32 v1, v54 offset:3168
	ds_write_b32 v1, v55 offset:3172
	ds_write_b32 v1, v56 offset:3176
	ds_write_b32 v1, v57 offset:3180
	ds_write_b32 v1, v58 offset:4224
	ds_write_b32 v1, v59 offset:4228
	ds_write_b32 v1, v60 offset:4232
	ds_write_b32 v1, v61 offset:4236
	ds_write_b32 v1, v62 offset:5280
	ds_write_b32 v1, v63 offset:5284
	ds_write_b32 v1, v64 offset:5288
	ds_write_b32 v1, v65 offset:5292
	ds_write_b32 v1, v66 offset:6336
	ds_write_b32 v1, v67 offset:6340
	ds_write_b32 v1, v68 offset:6344
	ds_write_b32 v1, v69 offset:6348
	ds_write_b32 v1, v70 offset:7392
	ds_write_b32 v1, v71 offset:7396
	ds_write_b32 v1, v72 offset:7400
	ds_write_b32 v1, v73 offset:7404
	v_mad_u32_u24 v9, v5, s23, v6
	s_lshl_b32 s46, s23, 3
	s_waitcnt lgkmcnt(0)
	ds_read_b32 v74, v2 offset:0
	ds_read_b32 v75, v2 offset:132
	ds_read_b32 v76, v2 offset:264
	ds_read_b32 v77, v2 offset:396
	ds_read_b32 v78, v2 offset:528
	ds_read_b32 v79, v2 offset:660
	ds_read_b32 v80, v2 offset:792
	ds_read_b32 v81, v2 offset:924
	ds_read_b32 v82, v2 offset:32
	ds_read_b32 v83, v2 offset:164
	ds_read_b32 v84, v2 offset:296
	ds_read_b32 v85, v2 offset:428
	ds_read_b32 v86, v2 offset:560
	ds_read_b32 v87, v2 offset:692
	ds_read_b32 v88, v2 offset:824
	ds_read_b32 v89, v2 offset:956
	s_waitcnt lgkmcnt(8)
	v_cvt_pk_bf16_f32 v106, v74, v75
	v_cvt_pk_bf16_f32 v107, v76, v77
	v_cvt_pk_bf16_f32 v108, v78, v79
	v_cvt_pk_bf16_f32 v109, v80, v81
	global_store_dwordx4 v9, v[106:109], s[20:21]
	s_add_u32 s20, s20, s46
	s_addc_u32 s21, s21, 0
	ds_read_b32 v90, v2 offset:64
	ds_read_b32 v91, v2 offset:196
	ds_read_b32 v92, v2 offset:328
	ds_read_b32 v93, v2 offset:460
	ds_read_b32 v94, v2 offset:592
	ds_read_b32 v95, v2 offset:724
	ds_read_b32 v96, v2 offset:856
	ds_read_b32 v97, v2 offset:988
	s_waitcnt lgkmcnt(8)
	v_cvt_pk_bf16_f32 v110, v82, v83
	v_cvt_pk_bf16_f32 v111, v84, v85
	v_cvt_pk_bf16_f32 v112, v86, v87
	v_cvt_pk_bf16_f32 v113, v88, v89
	global_store_dwordx4 v9, v[110:113], s[20:21]
	s_add_u32 s20, s20, s46
	s_addc_u32 s21, s21, 0
	ds_read_b32 v98, v2 offset:96
	ds_read_b32 v99, v2 offset:228
	ds_read_b32 v100, v2 offset:360
	ds_read_b32 v101, v2 offset:492
	ds_read_b32 v102, v2 offset:624
	ds_read_b32 v103, v2 offset:756
	ds_read_b32 v104, v2 offset:888
	ds_read_b32 v105, v2 offset:1020
	s_waitcnt lgkmcnt(8)
	v_cvt_pk_bf16_f32 v106, v90, v91
	v_cvt_pk_bf16_f32 v107, v92, v93
	v_cvt_pk_bf16_f32 v108, v94, v95
	v_cvt_pk_bf16_f32 v109, v96, v97
	global_store_dwordx4 v9, v[106:109], s[20:21]
	s_add_u32 s20, s20, s46
	s_addc_u32 s21, s21, 0
	s_waitcnt lgkmcnt(0)
	v_cvt_pk_bf16_f32 v110, v98, v99
	v_cvt_pk_bf16_f32 v111, v100, v101
	v_cvt_pk_bf16_f32 v112, v102, v103
	v_cvt_pk_bf16_f32 v113, v104, v105
	global_store_dwordx4 v9, v[110:113], s[20:21]
	s_cmp_eq_u32 s24, 0
	s_cbranch_scc1 .Ltr_done
	s_branch .Ltr_loop
